# attention tile loop: 80 packed f32 VALU ops (v_pk_mul/add/fma_f32) split into scalar pairs, bit-identical; on top of v23
# speedup vs baseline: 1.0056x; 1.0056x over previous
; __device__ __forceinline__ float max3f(float a, float b, float c) { float r; asm("v_max3_f32 %0, %1, %2, %3" : "=v"(r) : "v"(a), "v"(b), "v"(c)); return r; }
; __device__ __forceinline__ void softmax_step(f32x16& p0, f32x16& p1, float& m, float& l, f32x16 (&o)[2], u32x4 (&pw)[4]) {
;     float ra = max3f(p0[0], p0[1], p1[0]), rb = max3f(p0[2], p0[3], p1[1]); ra = max3f(ra, p1[2], p1[3]);
; #pragma unroll
;     for (int r = 4; r < 16; r += 4) { ra = max3f(ra, p0[r], p0[r + 1]); rb = max3f(rb, p0[r + 2], p0[r + 3]); ra = max3f(ra, p1[r], p1[r + 1]); rb = max3f(rb, p1[r + 2], p1[r + 3]); }
;     float rm = fmaxf(ra, rb);
;     { auto rr = __builtin_amdgcn_permlane32_swap(__float_as_uint(rm), __float_as_uint(rm), false, false); rm = fmaxf(__uint_as_float(rr[0]), __uint_as_float(rr[1])); }
;     if (__any(rm > ATT_THR)) {
;         const float dl = fmaxf(rm, 0.f), f = __builtin_amdgcn_exp2f(-dl); m += dl; l *= f;
; #pragma unroll
;         for (int r = 0; r < 16; ++r) { p0[r] -= dl; p1[r] -= dl; o[0][r] *= f; o[1][r] *= f; }
;     }
.LBB0_663:
	v_max3_f32 v2, v128, v129, v112
	v_max3_f32 v3, v130, v131, v113
	s_nop 0
	v_max3_f32 v2, v2, v114, v115
	v_max3_f32 v3, v3, v134, v135
	s_nop 0
	v_max3_f32 v2, v2, v132, v133
	v_max3_f32 v3, v3, v118, v119
	s_nop 0
	v_max3_f32 v2, v2, v116, v117
	v_max3_f32 v3, v3, v138, v139
	s_nop 0
	v_max3_f32 v2, v2, v136, v137
	v_max3_f32 v3, v3, v122, v123
	s_nop 0
	v_max3_f32 v2, v2, v120, v121
	v_max3_f32 v3, v3, v142, v143
	s_nop 0
	v_max3_f32 v2, v2, v140, v141
	v_max3_f32 v3, v3, v126, v127
	s_nop 0
	v_max3_f32 v2, v2, v124, v125
	v_max_f32_e32 v3, v3, v3
	v_max_f32_e32 v2, v2, v2
	v_max_f32_e32 v2, v2, v3
	v_mov_b32_e32 v3, v2
	s_nop 1
	v_permlane32_swap_b32_e32 v2, v3
	v_max_f32_e32 v3, v3, v3
	v_max_f32_e32 v2, v2, v2
	v_max_f32_e32 v2, v2, v3
	v_cmp_lt_f32_e32 vcc, s53, v2
	s_cbranch_vccz .LBB0_665
	v_max_f32_e32 v2, v2, v2
	v_max_f32_e32 v2, 0, v2
	v_exp_f32_e64 v4, -v2
	v_add_f32_e32 v202, v202, v2
	v_sub_f32_e32 v128, v128, v2
	v_sub_f32_e32 v129, v129, v2
	v_sub_f32_e32 v112, v112, v2
	v_sub_f32_e32 v113, v113, v2
	v_mul_f32_e32 v181, v181, v4
	v_sub_f32_e32 v130, v130, v2
	v_sub_f32_e32 v131, v131, v2
	v_sub_f32_e32 v114, v114, v2
	v_sub_f32_e32 v115, v115, v2
	v_sub_f32_e32 v132, v132, v2
	v_sub_f32_e32 v133, v133, v2
	v_sub_f32_e32 v116, v116, v2
	v_sub_f32_e32 v117, v117, v2
	v_sub_f32_e32 v134, v134, v2
	v_sub_f32_e32 v135, v135, v2
	v_sub_f32_e32 v118, v118, v2
	v_sub_f32_e32 v119, v119, v2
	v_sub_f32_e32 v136, v136, v2
	v_sub_f32_e32 v137, v137, v2
	v_sub_f32_e32 v120, v120, v2
	v_sub_f32_e32 v121, v121, v2
	v_sub_f32_e32 v138, v138, v2
	v_sub_f32_e32 v139, v139, v2
	v_sub_f32_e32 v122, v122, v2
	v_sub_f32_e32 v123, v123, v2
	v_sub_f32_e32 v140, v140, v2
	v_sub_f32_e32 v141, v141, v2
	v_sub_f32_e32 v124, v124, v2
	v_sub_f32_e32 v125, v125, v2
	v_sub_f32_e32 v142, v142, v2
	v_sub_f32_e32 v143, v143, v2
	v_sub_f32_e32 v126, v126, v2
	v_sub_f32_e32 v127, v127, v2
	v_mul_f32_e32 v78, v78, v4
	v_mul_f32_e32 v79, v79, v4
	v_mul_f32_e32 v76, v76, v4
	v_mul_f32_e32 v77, v77, v4
	v_mul_f32_e32 v74, v74, v4
	v_mul_f32_e32 v75, v75, v4
	v_mul_f32_e32 v72, v72, v4
	v_mul_f32_e32 v73, v73, v4
	v_mul_f32_e32 v70, v70, v4
	v_mul_f32_e32 v71, v71, v4
	v_mul_f32_e32 v68, v68, v4
	v_mul_f32_e32 v69, v69, v4
	v_mul_f32_e32 v66, v66, v4
	v_mul_f32_e32 v67, v67, v4
	v_mul_f32_e32 v64, v64, v4
	v_mul_f32_e32 v65, v65, v4
	v_mul_f32_e32 v62, v62, v4
	v_mul_f32_e32 v63, v63, v4
	v_mul_f32_e32 v60, v60, v4
	v_mul_f32_e32 v61, v61, v4
	v_mul_f32_e32 v58, v58, v4
	v_mul_f32_e32 v59, v59, v4
	v_mul_f32_e32 v56, v56, v4
	v_mul_f32_e32 v57, v57, v4
	v_mul_f32_e32 v54, v54, v4
	v_mul_f32_e32 v55, v55, v4
	v_mul_f32_e32 v52, v52, v4
	v_mul_f32_e32 v53, v53, v4
	v_mul_f32_e32 v50, v50, v4
	v_mul_f32_e32 v51, v51, v4
	v_mul_f32_e32 v48, v48, v4
	v_mul_f32_e32 v49, v49, v4
.LBB0_665:
	v_max3_f32 v2, v96, v97, v80
	v_max3_f32 v3, v98, v99, v81
	s_nop 0
	v_max3_f32 v2, v2, v82, v83
	v_max3_f32 v3, v3, v102, v103
	s_nop 0
	v_max3_f32 v2, v2, v100, v101
	v_max3_f32 v3, v3, v86, v87
	s_nop 0
	v_max3_f32 v2, v2, v84, v85
	v_max3_f32 v3, v3, v106, v107
	s_nop 0
	v_max3_f32 v2, v2, v104, v105
	v_max3_f32 v3, v3, v90, v91
	s_nop 0
	v_max3_f32 v2, v2, v88, v89
	v_max3_f32 v3, v3, v110, v111
	s_nop 0
	v_max3_f32 v2, v2, v108, v109
	v_max3_f32 v3, v3, v94, v95
	s_nop 0
	v_max3_f32 v2, v2, v92, v93
	v_max_f32_e32 v3, v3, v3
	v_max_f32_e32 v2, v2, v2
	v_max_f32_e32 v2, v2, v3
	v_mov_b32_e32 v3, v2
	s_nop 1
	v_permlane32_swap_b32_e32 v2, v3
	v_max_f32_e32 v3, v3, v3
	v_max_f32_e32 v2, v2, v2
	v_max_f32_e32 v2, v2, v3
	v_cmp_lt_f32_e32 vcc, s53, v2
	s_cbranch_vccz .LBB0_667
	v_max_f32_e32 v2, v2, v2
	v_max_f32_e32 v2, 0, v2
	v_exp_f32_e64 v4, -v2
	v_add_f32_e32 v201, v201, v2
	v_sub_f32_e32 v96, v96, v2
	v_sub_f32_e32 v97, v97, v2
	v_sub_f32_e32 v80, v80, v2
	v_sub_f32_e32 v81, v81, v2
	v_mul_f32_e32 v173, v173, v4
	v_sub_f32_e32 v98, v98, v2
	v_sub_f32_e32 v99, v99, v2
	v_sub_f32_e32 v82, v82, v2
	v_sub_f32_e32 v83, v83, v2
	v_sub_f32_e32 v100, v100, v2
	v_sub_f32_e32 v101, v101, v2
	v_sub_f32_e32 v84, v84, v2
	v_sub_f32_e32 v85, v85, v2
	v_sub_f32_e32 v102, v102, v2
	v_sub_f32_e32 v103, v103, v2
	v_sub_f32_e32 v86, v86, v2
	v_sub_f32_e32 v87, v87, v2
	v_sub_f32_e32 v104, v104, v2
	v_sub_f32_e32 v105, v105, v2
	v_sub_f32_e32 v88, v88, v2
	v_sub_f32_e32 v89, v89, v2
	v_sub_f32_e32 v106, v106, v2
	v_sub_f32_e32 v107, v107, v2
	v_sub_f32_e32 v90, v90, v2
	v_sub_f32_e32 v91, v91, v2
	v_sub_f32_e32 v108, v108, v2
	v_sub_f32_e32 v109, v109, v2
	v_sub_f32_e32 v92, v92, v2
	v_sub_f32_e32 v93, v93, v2
	v_sub_f32_e32 v110, v110, v2
	v_sub_f32_e32 v111, v111, v2
	v_sub_f32_e32 v94, v94, v2
	v_sub_f32_e32 v95, v95, v2
	v_mul_f32_e32 v46, v46, v4
	v_mul_f32_e32 v47, v47, v4
	v_mul_f32_e32 v44, v44, v4
	v_mul_f32_e32 v45, v45, v4
	v_mul_f32_e32 v42, v42, v4
	v_mul_f32_e32 v43, v43, v4
	v_mul_f32_e32 v40, v40, v4
	v_mul_f32_e32 v41, v41, v4
	v_mul_f32_e32 v38, v38, v4
	v_mul_f32_e32 v39, v39, v4
	v_mul_f32_e32 v36, v36, v4
	v_mul_f32_e32 v37, v37, v4
	v_mul_f32_e32 v34, v34, v4
	v_mul_f32_e32 v35, v35, v4
	v_mul_f32_e32 v32, v32, v4
	v_mul_f32_e32 v33, v33, v4
	v_mul_f32_e32 v30, v30, v4
	v_mul_f32_e32 v31, v31, v4
	v_mul_f32_e32 v28, v28, v4
	v_mul_f32_e32 v29, v29, v4
	v_mul_f32_e32 v26, v26, v4
	v_mul_f32_e32 v27, v27, v4
	v_mul_f32_e32 v24, v24, v4
	v_mul_f32_e32 v25, v25, v4
	v_mul_f32_e32 v22, v22, v4
	v_mul_f32_e32 v23, v23, v4
	v_mul_f32_e32 v20, v20, v4
	v_mul_f32_e32 v21, v21, v4
	v_mul_f32_e32 v18, v18, v4
	v_mul_f32_e32 v19, v19, v4
	v_mul_f32_e32 v16, v16, v4
	v_mul_f32_e32 v17, v17, v4
; #define LAS __attribute__((address_space(3)))
; __device__ __forceinline__ unsigned cvtpk(float lo, float hi) { f32x2_t v = {lo, hi}; bf16x2_t b = __builtin_convertvector(v, bf16x2_t); return __builtin_bit_cast(unsigned, b); }
; __device__ __forceinline__ s16x4 vtr(const LAS unsigned char* p) { return __builtin_bit_cast(s16x4, __builtin_amdgcn_ds_read_tr16_b64_v4i16((LAS v4i16_t*)p)); }
; __device__ __forceinline__ unsigned cvtpk(float lo, float hi) { f32x2_t v = {lo, hi}; bf16x2_t b = __builtin_convertvector(v, bf16x2_t); return __builtin_bit_cast(unsigned, b); }
; __device__ __forceinline__ s16x4 vtr(const LAS unsigned char* p) { return __builtin_bit_cast(s16x4, __builtin_amdgcn_ds_read_tr16_b64_v4i16((LAS v4i16_t*)p)); }
; __device__ __forceinline__ void softmax_step(f32x16& p0, f32x16& p1, float& m, float& l, f32x16 (&o)[2], u32x4 (&pw)[4]) {
;     ...
;     float sa = 0.f, sb = 0.f;
; #pragma unroll
;     for (int r = 0; r < 16; ++r) { p0[r] = __builtin_amdgcn_exp2f(p0[r]); p1[r] = __builtin_amdgcn_exp2f(p1[r]); sa += p0[r]; sb += p1[r]; }
;     l += sa + sb;
;     pw[0] = (u32x4){cvtpk(p0[0], p0[1]), cvtpk(p0[2], p0[3]), cvtpk(p0[4], p0[5]), cvtpk(p0[6], p0[7])};
;     pw[1] = (u32x4){cvtpk(p0[8], p0[9]), cvtpk(p0[10], p0[11]), cvtpk(p0[12], p0[13]), cvtpk(p0[14], p0[15])};
;     pw[2] = (u32x4){cvtpk(p1[0], p1[1]), cvtpk(p1[2], p1[3]), cvtpk(p1[4], p1[5]), cvtpk(p1[6], p1[7])};
;     pw[3] = (u32x4){cvtpk(p1[8], p1[9]), cvtpk(p1[10], p1[11]), cvtpk(p1[12], p1[13]), cvtpk(p1[14], p1[15])};
; __device__ __forceinline__ void attn_unit(Frame& F, const Ptrs& P, int u, int u_next, bf16x8 (&qa)[4], ScanRider& R) {
;     ...
;         const LAS unsigned char* vb = vb0 + j * 8192;
; #pragma unroll
;         for (int d0 = 0; d0 < 2; ++d0)
; #pragma unroll
;             for (int ks = 0; ks < 4; ++ks) {
;                 const s16x4 vl = vtr(vb + d0 * 4096 + ks * 1024), vh = vtr(vb + d0 * 4096 + ks * 1024 + 512);
;                 const bf16x8 vf = (bf16x8){vl[0], vl[1], vl[2], vl[3], vh[0], vh[1], vh[2], vh[3]};
;                 oA[d0] = __builtin_amdgcn_mfma_f32_32x32x16_bf16(vf, __builtin_bit_cast(bf16x8, pwA[ks]), oA[d0], 0, 0, 0);
;                 oB[d0] = __builtin_amdgcn_mfma_f32_32x32x16_bf16(vf, __builtin_bit_cast(bf16x8, pwB[ks]), oB[d0], 0, 0, 0);
;             }
.LBB0_667:
	v_add_u32_e32 v236, s52, v196
	v_exp_f32_e32 v128, v128
	v_exp_f32_e32 v129, v129
	v_exp_f32_e32 v130, v130
	v_exp_f32_e32 v131, v131
	v_exp_f32_e32 v132, v132
	v_exp_f32_e32 v133, v133
	v_exp_f32_e32 v134, v134
	v_exp_f32_e32 v135, v135
	ds_read_b64_tr_b16 v[212:213], v236 offset:49152
	ds_read_b64_tr_b16 v[214:215], v236 offset:49664
	v_exp_f32_e32 v208, v96
	v_exp_f32_e32 v207, v97
	v_exp_f32_e32 v98, v98
	v_exp_f32_e32 v97, v99
	v_exp_f32_e32 v96, v100
	v_exp_f32_e32 v210, v101
	v_exp_f32_e32 v209, v102
	v_exp_f32_e32 v101, v103
	v_exp_f32_e32 v203, v112
	v_exp_f32_e32 v204, v113
	v_exp_f32_e32 v205, v114
	v_exp_f32_e32 v206, v115
	v_cvt_pk_bf16_f32 v112, v128, v129
	v_cvt_pk_bf16_f32 v113, v130, v131
	v_cvt_pk_bf16_f32 v114, v132, v133
	v_cvt_pk_bf16_f32 v115, v134, v135
	v_cvt_pk_bf16_f32 v220, v208, v207
	v_cvt_pk_bf16_f32 v221, v98, v97
	v_cvt_pk_bf16_f32 v222, v96, v210
	v_cvt_pk_bf16_f32 v223, v209, v101
	s_waitcnt lgkmcnt(0)
	v_mfma_f32_32x32x16_bf16 v[64:79], v[212:215], v[112:115], v[64:79]
	v_exp_f32_e32 v136, v136
	v_exp_f32_e32 v137, v137
	v_exp_f32_e32 v138, v138
	v_exp_f32_e32 v139, v139
	v_exp_f32_e32 v140, v140
	v_exp_f32_e32 v141, v141
	v_exp_f32_e32 v142, v142
	v_mfma_f32_32x32x16_bf16 v[32:47], v[212:215], v[220:223], v[32:47]
	v_exp_f32_e32 v143, v143
	ds_read_b64_tr_b16 v[216:217], v236 offset:50176
	ds_read_b64_tr_b16 v[218:219], v236 offset:50688
	v_exp_f32_e32 v211, v104
	v_exp_f32_e32 v105, v105
	v_exp_f32_e32 v104, v106
	v_exp_f32_e32 v103, v107
	v_exp_f32_e32 v102, v108
	v_exp_f32_e32 v100, v109
	v_exp_f32_e32 v99, v110
	v_exp_f32_e32 v106, v111
	v_cvt_pk_bf16_f32 v10, v136, v137
	v_cvt_pk_bf16_f32 v11, v138, v139
	v_cvt_pk_bf16_f32 v12, v140, v141
	v_cvt_pk_bf16_f32 v13, v142, v143
	v_cvt_pk_bf16_f32 v212, v211, v105
	v_cvt_pk_bf16_f32 v213, v104, v103
	v_cvt_pk_bf16_f32 v214, v102, v100
	v_cvt_pk_bf16_f32 v215, v99, v106
	s_waitcnt lgkmcnt(0)
	v_mfma_f32_32x32x16_bf16 v[64:79], v[216:219], v[10:13], v[64:79]
	v_exp_f32_e32 v116, v116
	v_exp_f32_e32 v117, v117
	v_exp_f32_e32 v118, v118
	v_exp_f32_e32 v119, v119
	ds_read_b64_tr_b16 v[224:225], v236 offset:51200
	ds_read_b64_tr_b16 v[226:227], v236 offset:51712
	v_exp_f32_e32 v108, v80
	v_exp_f32_e32 v107, v81
	v_mfma_f32_32x32x16_bf16 v[32:47], v[216:219], v[212:215], v[32:47]
	v_exp_f32_e32 v82, v82
	v_exp_f32_e32 v81, v83
	v_exp_f32_e32 v80, v84
	v_exp_f32_e32 v85, v85
	v_exp_f32_e32 v84, v86
	v_exp_f32_e32 v83, v87
	v_cvt_pk_bf16_f32 v6, v203, v204
	v_cvt_pk_bf16_f32 v7, v205, v206
	v_cvt_pk_bf16_f32 v8, v116, v117
	v_cvt_pk_bf16_f32 v9, v118, v119
	v_cvt_pk_bf16_f32 v228, v108, v107
	v_cvt_pk_bf16_f32 v229, v82, v81
	v_cvt_pk_bf16_f32 v230, v80, v85
	v_cvt_pk_bf16_f32 v231, v84, v83
	s_waitcnt lgkmcnt(0)
	v_mfma_f32_32x32x16_bf16 v[64:79], v[224:227], v[6:9], v[64:79]
	v_exp_f32_e32 v120, v120
	v_exp_f32_e32 v121, v121
	v_exp_f32_e32 v122, v122
	v_exp_f32_e32 v123, v123
	v_exp_f32_e32 v124, v124
	v_exp_f32_e32 v125, v125
	v_exp_f32_e32 v126, v126
	v_mfma_f32_32x32x16_bf16 v[32:47], v[224:227], v[228:231], v[32:47]
	v_exp_f32_e32 v127, v127
	ds_read_b64_tr_b16 v[216:217], v236 offset:52224
	ds_read_b64_tr_b16 v[218:219], v236 offset:52736
	v_exp_f32_e32 v109, v88
	v_exp_f32_e32 v89, v89
	v_exp_f32_e32 v88, v90
	v_exp_f32_e32 v87, v91
	v_exp_f32_e32 v86, v92
	v_exp_f32_e32 v92, v93
	v_exp_f32_e32 v91, v94
	v_exp_f32_e32 v90, v95
	v_cvt_pk_bf16_f32 v2, v120, v121
	v_cvt_pk_bf16_f32 v3, v122, v123
	v_cvt_pk_bf16_f32 v4, v124, v125
	v_cvt_pk_bf16_f32 v5, v126, v127
	v_cvt_pk_bf16_f32 v224, v109, v89
	v_cvt_pk_bf16_f32 v225, v88, v87
	v_cvt_pk_bf16_f32 v226, v86, v92
	v_cvt_pk_bf16_f32 v227, v91, v90
	s_waitcnt lgkmcnt(0)
	v_mfma_f32_32x32x16_bf16 v[64:79], v[216:219], v[2:5], v[64:79]
	v_mfma_f32_32x32x16_bf16 v[32:47], v[216:219], v[224:227], v[32:47]
	ds_read_b64_tr_b16 v[216:217], v236 offset:53248
	ds_read_b64_tr_b16 v[218:219], v236 offset:53760
	ds_read_b64_tr_b16 v[232:233], v236 offset:54272
	ds_read_b64_tr_b16 v[234:235], v236 offset:54784
	s_waitcnt lgkmcnt(2)
	v_mfma_f32_32x32x16_bf16 v[48:63], v[216:219], v[112:115], v[48:63]
	v_mfma_f32_32x32x16_bf16 v[16:31], v[216:219], v[220:223], v[16:31]
	s_waitcnt lgkmcnt(0)
	v_mfma_f32_32x32x16_bf16 v[48:63], v[232:235], v[10:13], v[48:63]
	ds_read_b64_tr_b16 v[10:11], v236 offset:55296
	ds_read_b64_tr_b16 v[12:13], v236 offset:55808
	ds_read_b64_tr_b16 v[110:111], v236 offset:56320
	ds_read_b64_tr_b16 v[112:113], v236 offset:56832
	v_mfma_f32_32x32x16_bf16 v[16:31], v[232:235], v[212:215], v[16:31]
	s_waitcnt lgkmcnt(2)
	v_mfma_f32_32x32x16_bf16 v[48:63], v[10:13], v[6:9], v[48:63]
	v_mfma_f32_32x32x16_bf16 v[16:31], v[10:13], v[228:231], v[16:31]
	s_waitcnt lgkmcnt(0)
	v_mfma_f32_32x32x16_bf16 v[48:63], v[110:113], v[2:5], v[48:63]
	v_mfma_f32_32x32x16_bf16 v[16:31], v[110:113], v[224:227], v[16:31]
	s_andn2_b64 vcc, exec, s[28:29]
	s_cbranch_vccnz .LBB0_650
; __device__ __forceinline__ unsigned cvtpk(float lo, float hi) { f32x2_t v = {lo, hi}; bf16x2_t b = __builtin_convertvector(v, bf16x2_t); return __builtin_bit_cast(unsigned, b); }
; __device__ __forceinline__ float lo16(unsigned u) { return __uint_as_float(u << 16); }
; __device__ __forceinline__ float hi16(unsigned u) { return __uint_as_float(u & 0xffff0000u); }
; __device__ __forceinline__ unsigned cvtpk(float lo, float hi) { f32x2_t v = {lo, hi}; bf16x2_t b = __builtin_convertvector(v, bf16x2_t); return __builtin_bit_cast(unsigned, b); }
; __device__ __forceinline__ float lo16(unsigned u) { return __uint_as_float(u << 16); }
; __device__ __forceinline__ float hi16(unsigned u) { return __uint_as_float(u & 0xffff0000u); }
; __device__ __forceinline__ void attn_unit(Frame& F, const Ptrs& P, int u, int u_next, bf16x8 (&qa)[4], ScanRider& R) {
;     ...
;         if (sc_on) {
;             unsigned char* SBw = (unsigned char*)P.out;
; #pragma unroll
;             for (int k = 0; k < 8; ++k) { const int i = R.i0 + k, c = R.dir ? 63 - i : i; const size_t bo = ((((size_t)R.b * 64 + c) * 2 + R.dir) * 16 + R.h);
;                 u32x2 o; o.x = cvtpk(R.s0, R.s1); o.y = cvtpk(R.s2, R.s3);
;                 *(u32x2*)(SBw + bo * 16384 + R.quarter * 4096 + (size_t)svoff) = o;
;                 R.s0 = R.s0 * sd[k] + lo16(sv[k].x); R.s1 = R.s1 * sd[k] + hi16(sv[k].x); R.s2 = R.s2 * sd[k] + lo16(sv[k].y); R.s3 = R.s3 * sd[k] + hi16(sv[k].y); }
;             R.i0 += 8;
;         }
	s_sub_i32 s28, 63, s78
	s_and_b64 s[4:5], s[8:9], exec
	s_cselect_b32 s4, s78, s28
	s_ashr_i32 s5, s4, 31
	s_lshl_b64 s[4:5], s[4:5], 19
	s_add_u32 s4, s46, s4
	v_cvt_pk_bf16_f32 v2, v162, v163
	v_cvt_pk_bf16_f32 v3, v160, v161
	s_addc_u32 s5, s47, s5
	s_add_i32 s28, s78, 1
	s_sub_i32 s29, 62, s78
	global_store_dwordx2 v0, v[2:3], s[4:5]
	s_and_b64 s[4:5], s[8:9], exec
	s_cselect_b32 s4, s28, s29
	s_ashr_i32 s5, s4, 31
	s_waitcnt vmcnt(15)
	v_lshlrev_b32_e32 v2, 16, v164
	v_and_b32_e32 v3, 0xffff0000, v164
	v_lshlrev_b32_e32 v4, 16, v165
	v_and_b32_e32 v5, 0xffff0000, v165
	s_lshl_b64 s[4:5], s[4:5], 19
	v_fma_f32 v2, v162, v166, v2
	v_fma_f32 v3, v163, v166, v3
	v_fma_f32 v4, v160, v166, v4
	v_fma_f32 v5, v161, v166, v5
	s_add_u32 s4, s46, s4
	v_cvt_pk_bf16_f32 v6, v2, v3
	v_cvt_pk_bf16_f32 v7, v4, v5
	s_addc_u32 s5, s47, s5
	s_add_i32 s28, s78, 2
	s_sub_i32 s29, 61, s78
	global_store_dwordx2 v0, v[6:7], s[4:5]
	s_and_b64 s[4:5], s[8:9], exec
	s_cselect_b32 s4, s28, s29
	s_waitcnt vmcnt(14)
	v_lshlrev_b32_e32 v6, 16, v170
	v_and_b32_e32 v7, 0xffff0000, v170
	s_ashr_i32 s5, s4, 31
	v_fma_f32 v2, v168, v2, v6
	v_fma_f32 v3, v168, v3, v7
	v_lshlrev_b32_e32 v6, 16, v171
	v_and_b32_e32 v7, 0xffff0000, v171
	s_lshl_b64 s[4:5], s[4:5], 19
	v_fma_f32 v4, v168, v4, v6
	v_fma_f32 v5, v168, v5, v7
	s_add_u32 s4, s46, s4
	v_cvt_pk_bf16_f32 v6, v2, v3
	v_cvt_pk_bf16_f32 v7, v4, v5
	s_addc_u32 s5, s47, s5
	s_add_i32 s28, s78, 3
	s_sub_i32 s29, 60, s78
	global_store_dwordx2 v0, v[6:7], s[4:5]
	s_and_b64 s[4:5], s[8:9], exec
	s_cselect_b32 s4, s28, s29
	s_waitcnt vmcnt(13)
	v_lshlrev_b32_e32 v6, 16, v174
	v_and_b32_e32 v7, 0xffff0000, v174
	s_ashr_i32 s5, s4, 31
	v_fma_f32 v2, v172, v2, v6
	v_fma_f32 v3, v172, v3, v7
	v_lshlrev_b32_e32 v6, 16, v175
	v_and_b32_e32 v7, 0xffff0000, v175
	s_lshl_b64 s[4:5], s[4:5], 19
	v_fma_f32 v4, v172, v4, v6
	v_fma_f32 v5, v172, v5, v7
	s_add_u32 s4, s46, s4
	v_cvt_pk_bf16_f32 v6, v2, v3
	v_cvt_pk_bf16_f32 v7, v4, v5
	s_addc_u32 s5, s47, s5
	s_add_i32 s28, s78, 4
	s_sub_i32 s29, 59, s78
	global_store_dwordx2 v0, v[6:7], s[4:5]
	s_and_b64 s[4:5], s[8:9], exec
	s_cselect_b32 s4, s28, s29
	s_waitcnt vmcnt(12)
	v_lshlrev_b32_e32 v6, 16, v178
	v_and_b32_e32 v7, 0xffff0000, v178
	s_ashr_i32 s5, s4, 31
	v_fma_f32 v2, v176, v2, v6
	v_fma_f32 v3, v176, v3, v7
	v_lshlrev_b32_e32 v6, 16, v179
	v_and_b32_e32 v7, 0xffff0000, v179
	s_lshl_b64 s[4:5], s[4:5], 19
	v_fma_f32 v4, v176, v4, v6
	v_fma_f32 v5, v176, v5, v7
	s_add_u32 s4, s46, s4
	v_cvt_pk_bf16_f32 v6, v2, v3
	v_cvt_pk_bf16_f32 v7, v4, v5
	s_addc_u32 s5, s47, s5
	s_add_i32 s28, s78, 5
	s_sub_i32 s29, 58, s78
	global_store_dwordx2 v0, v[6:7], s[4:5]
	s_and_b64 s[4:5], s[8:9], exec
	s_cselect_b32 s4, s28, s29
	s_waitcnt vmcnt(11)
	v_lshlrev_b32_e32 v6, 16, v182
	v_and_b32_e32 v7, 0xffff0000, v182
	s_ashr_i32 s5, s4, 31
	v_fma_f32 v2, v180, v2, v6
	v_fma_f32 v3, v180, v3, v7
	v_lshlrev_b32_e32 v6, 16, v183
	v_and_b32_e32 v7, 0xffff0000, v183
	s_lshl_b64 s[4:5], s[4:5], 19
	v_fma_f32 v4, v180, v4, v6
	v_fma_f32 v5, v180, v5, v7
	s_add_u32 s4, s46, s4
	v_cvt_pk_bf16_f32 v6, v2, v3
	v_cvt_pk_bf16_f32 v7, v4, v5
	s_addc_u32 s5, s47, s5
	s_add_i32 s28, s78, 6
	s_sub_i32 s29, 57, s78
	global_store_dwordx2 v0, v[6:7], s[4:5]
	s_and_b64 s[4:5], s[8:9], exec
	s_cselect_b32 s4, s28, s29
	s_waitcnt vmcnt(10)
	v_lshlrev_b32_e32 v6, 16, v186
	v_and_b32_e32 v7, 0xffff0000, v186
	s_ashr_i32 s5, s4, 31
	v_fma_f32 v2, v184, v2, v6
	v_fma_f32 v3, v184, v3, v7
	v_lshlrev_b32_e32 v6, 16, v187
	v_and_b32_e32 v7, 0xffff0000, v187
	s_lshl_b64 s[4:5], s[4:5], 19
	v_fma_f32 v4, v184, v4, v6
	v_fma_f32 v5, v184, v5, v7
	s_add_u32 s4, s46, s4
	v_cvt_pk_bf16_f32 v6, v2, v3
	v_cvt_pk_bf16_f32 v7, v4, v5
	s_addc_u32 s5, s47, s5
	s_add_i32 s28, s78, 7
	s_sub_i32 s29, 56, s78
	global_store_dwordx2 v0, v[6:7], s[4:5]
	s_and_b64 s[4:5], s[8:9], exec
	s_cselect_b32 s4, s28, s29
	s_waitcnt vmcnt(9)
	v_lshlrev_b32_e32 v6, 16, v190
	v_and_b32_e32 v7, 0xffff0000, v190
	s_ashr_i32 s5, s4, 31
	v_fma_f32 v2, v188, v2, v6
	v_fma_f32 v3, v188, v3, v7
	v_lshlrev_b32_e32 v6, 16, v191
	v_and_b32_e32 v7, 0xffff0000, v191
	s_lshl_b64 s[4:5], s[4:5], 19
	v_fma_f32 v4, v188, v4, v6
	v_fma_f32 v5, v188, v5, v7
	s_add_u32 s4, s46, s4
	v_cvt_pk_bf16_f32 v6, v2, v3
	v_cvt_pk_bf16_f32 v7, v4, v5
	s_addc_u32 s5, s47, s5
	global_store_dwordx2 v0, v[6:7], s[4:5]
	s_waitcnt vmcnt(9)
	v_lshlrev_b32_e32 v6, 16, v192
	v_and_b32_e32 v7, 0xffff0000, v192
	s_waitcnt vmcnt(8)
	v_fma_f32 v162, v194, v2, v6
	v_fma_f32 v163, v194, v3, v7
	v_lshlrev_b32_e32 v2, 16, v193
	v_and_b32_e32 v3, 0xffff0000, v193
	v_fma_f32 v160, v194, v4, v2
	v_fma_f32 v161, v194, v5, v3
	s_add_i32 s78, s78, 8
	s_branch .LBB0_650
